# attention loop rewritten: pipelined LDS fragment reads, permlane32 row-max, batched gate loads in epilogue
# speedup vs baseline: 1.0177x; 1.0177x over previous
.LBB0_43:
	v_ashrrev_i32_e32 v69, 31, v214
	v_mov_b32_e32 v68, v214
	v_lshlrev_b64 v[68:69], 12, v[68:69]
	v_lshl_or_b32 v68, s6, 8, v68
	v_lshl_add_u64 v[66:67], v[208:209], 0, v[68:69]
	v_lshl_add_u64 v[68:69], v[210:211], 0, v[68:69]
	global_load_dwordx2 v[144:145], v[66:67], off
	global_load_dwordx2 v[146:147], v[66:67], off offset:16
	global_load_dwordx2 v[148:149], v[66:67], off offset:32
	global_load_dwordx2 v[150:151], v[66:67], off offset:48
	global_load_dwordx2 v[152:153], v[66:67], off offset:64
	global_load_dwordx2 v[154:155], v[66:67], off offset:80
	global_load_dwordx2 v[156:157], v[66:67], off offset:96
	global_load_dwordx2 v[158:159], v[66:67], off offset:112
	global_load_dwordx2 v[160:161], v[66:67], off offset:128
	global_load_dwordx2 v[162:163], v[66:67], off offset:144
	global_load_dwordx2 v[164:165], v[66:67], off offset:160
	global_load_dwordx2 v[166:167], v[66:67], off offset:176
	global_load_dwordx2 v[168:169], v[66:67], off offset:192
	global_load_dwordx2 v[170:171], v[66:67], off offset:208
	global_load_dwordx2 v[172:173], v[66:67], off offset:224
	global_load_dwordx2 v[174:175], v[66:67], off offset:240
	v_cmp_lt_i32_e32 vcc, v228, v227
	s_nop 1
	v_cndmask_b32_e32 v64, v226, v228, vcc
	v_lshlrev_b32_e32 v64, 2, v64
	ds_bpermute_b32 v64, v64, v215
	s_waitcnt lgkmcnt(0)
	v_add_f32_e32 v64, v215, v64
	v_div_scale_f32 v65, s[2:3], v64, v64, 1.0
	v_rcp_f32_e32 v66, v65
	s_nop 1
	v_fma_f32 v67, -v65, v66, 1.0
	s_mov_b64 s[2:3], 0
	v_fmac_f32_e32 v66, v67, v66
	v_div_scale_f32 v67, vcc, 1.0, v64, 1.0
	v_mul_f32_e32 v78, v67, v66
	v_fma_f32 v79, -v65, v78, v67
	v_fmac_f32_e32 v78, v79, v66
	v_fma_f32 v65, -v65, v78, v67
	v_div_fmas_f32 v65, v65, v66, v78
	v_div_fixup_f32 v64, v65, v64, 1.0
	v_pk_mul_f32 v[48:49], v[48:49], v[64:65] op_sel_hi:[1,0]
	v_pk_mul_f32 v[50:51], v[50:51], v[64:65] op_sel_hi:[1,0]
	s_waitcnt vmcnt(15)
	v_lshlrev_b32_e32 v72, 16, v144
	v_and_b32_e32 v73, 0xffff0000, v144
	v_lshlrev_b32_e32 v74, 16, v145
	v_and_b32_e32 v75, 0xffff0000, v145
	v_pk_mul_f32 v[48:49], v[48:49], v[72:73]
	v_pk_mul_f32 v[50:51], v[50:51], v[74:75]
	v_cvt_pk_bf16_f32 v70, v48, v49
	v_cvt_pk_bf16_f32 v71, v50, v51
	global_store_dwordx2 v[68:69], v[70:71], off
	v_pk_mul_f32 v[52:53], v[52:53], v[64:65] op_sel_hi:[1,0]
	v_pk_mul_f32 v[54:55], v[54:55], v[64:65] op_sel_hi:[1,0]
	s_waitcnt vmcnt(15)
	v_lshlrev_b32_e32 v72, 16, v146
	v_and_b32_e32 v73, 0xffff0000, v146
	v_lshlrev_b32_e32 v74, 16, v147
	v_and_b32_e32 v75, 0xffff0000, v147
	v_pk_mul_f32 v[52:53], v[52:53], v[72:73]
	v_pk_mul_f32 v[54:55], v[54:55], v[74:75]
	v_cvt_pk_bf16_f32 v76, v52, v53
	v_cvt_pk_bf16_f32 v77, v54, v55
	global_store_dwordx2 v[68:69], v[76:77], off offset:16
	v_pk_mul_f32 v[56:57], v[56:57], v[64:65] op_sel_hi:[1,0]
	v_pk_mul_f32 v[58:59], v[58:59], v[64:65] op_sel_hi:[1,0]
	s_waitcnt vmcnt(15)
	v_lshlrev_b32_e32 v72, 16, v148
	v_and_b32_e32 v73, 0xffff0000, v148
	v_lshlrev_b32_e32 v74, 16, v149
	v_and_b32_e32 v75, 0xffff0000, v149
	v_pk_mul_f32 v[56:57], v[56:57], v[72:73]
	v_pk_mul_f32 v[58:59], v[58:59], v[74:75]
	v_cvt_pk_bf16_f32 v70, v56, v57
	v_cvt_pk_bf16_f32 v71, v58, v59
	global_store_dwordx2 v[68:69], v[70:71], off offset:32
	v_pk_mul_f32 v[60:61], v[60:61], v[64:65] op_sel_hi:[1,0]
	v_pk_mul_f32 v[62:63], v[62:63], v[64:65] op_sel_hi:[1,0]
	s_waitcnt vmcnt(15)
	v_lshlrev_b32_e32 v72, 16, v150
	v_and_b32_e32 v73, 0xffff0000, v150
	v_lshlrev_b32_e32 v74, 16, v151
	v_and_b32_e32 v75, 0xffff0000, v151
	v_pk_mul_f32 v[60:61], v[60:61], v[72:73]
	v_pk_mul_f32 v[62:63], v[62:63], v[74:75]
	v_cvt_pk_bf16_f32 v76, v60, v61
	v_cvt_pk_bf16_f32 v77, v62, v63
	global_store_dwordx2 v[68:69], v[76:77], off offset:48
	v_pk_mul_f32 v[32:33], v[32:33], v[64:65] op_sel_hi:[1,0]
	v_pk_mul_f32 v[34:35], v[34:35], v[64:65] op_sel_hi:[1,0]
	s_waitcnt vmcnt(15)
	v_lshlrev_b32_e32 v72, 16, v152
	v_and_b32_e32 v73, 0xffff0000, v152
	v_lshlrev_b32_e32 v74, 16, v153
	v_and_b32_e32 v75, 0xffff0000, v153
	v_pk_mul_f32 v[32:33], v[32:33], v[72:73]
	v_pk_mul_f32 v[34:35], v[34:35], v[74:75]
	v_cvt_pk_bf16_f32 v70, v32, v33
	v_cvt_pk_bf16_f32 v71, v34, v35
	global_store_dwordx2 v[68:69], v[70:71], off offset:64
	v_pk_mul_f32 v[36:37], v[36:37], v[64:65] op_sel_hi:[1,0]
	v_pk_mul_f32 v[38:39], v[38:39], v[64:65] op_sel_hi:[1,0]
	s_waitcnt vmcnt(15)
	v_lshlrev_b32_e32 v72, 16, v154
	v_and_b32_e32 v73, 0xffff0000, v154
	v_lshlrev_b32_e32 v74, 16, v155
	v_and_b32_e32 v75, 0xffff0000, v155
	v_pk_mul_f32 v[36:37], v[36:37], v[72:73]
	v_pk_mul_f32 v[38:39], v[38:39], v[74:75]
	v_cvt_pk_bf16_f32 v76, v36, v37
	v_cvt_pk_bf16_f32 v77, v38, v39
	global_store_dwordx2 v[68:69], v[76:77], off offset:80
	v_pk_mul_f32 v[40:41], v[40:41], v[64:65] op_sel_hi:[1,0]
	v_pk_mul_f32 v[42:43], v[42:43], v[64:65] op_sel_hi:[1,0]
	s_waitcnt vmcnt(15)
	v_lshlrev_b32_e32 v72, 16, v156
	v_and_b32_e32 v73, 0xffff0000, v156
	v_lshlrev_b32_e32 v74, 16, v157
	v_and_b32_e32 v75, 0xffff0000, v157
	v_pk_mul_f32 v[40:41], v[40:41], v[72:73]
	v_pk_mul_f32 v[42:43], v[42:43], v[74:75]
	v_cvt_pk_bf16_f32 v70, v40, v41
	v_cvt_pk_bf16_f32 v71, v42, v43
	global_store_dwordx2 v[68:69], v[70:71], off offset:96
	v_pk_mul_f32 v[44:45], v[44:45], v[64:65] op_sel_hi:[1,0]
	v_pk_mul_f32 v[46:47], v[46:47], v[64:65] op_sel_hi:[1,0]
	s_waitcnt vmcnt(15)
	v_lshlrev_b32_e32 v72, 16, v158
	v_and_b32_e32 v73, 0xffff0000, v158
	v_lshlrev_b32_e32 v74, 16, v159
	v_and_b32_e32 v75, 0xffff0000, v159
	v_pk_mul_f32 v[44:45], v[44:45], v[72:73]
	v_pk_mul_f32 v[46:47], v[46:47], v[74:75]
	v_cvt_pk_bf16_f32 v76, v44, v45
	v_cvt_pk_bf16_f32 v77, v46, v47
	global_store_dwordx2 v[68:69], v[76:77], off offset:112
	v_pk_mul_f32 v[16:17], v[16:17], v[64:65] op_sel_hi:[1,0]
	v_pk_mul_f32 v[18:19], v[18:19], v[64:65] op_sel_hi:[1,0]
	s_waitcnt vmcnt(15)
	v_lshlrev_b32_e32 v72, 16, v160
	v_and_b32_e32 v73, 0xffff0000, v160
	v_lshlrev_b32_e32 v74, 16, v161
	v_and_b32_e32 v75, 0xffff0000, v161
	v_pk_mul_f32 v[16:17], v[16:17], v[72:73]
	v_pk_mul_f32 v[18:19], v[18:19], v[74:75]
	v_cvt_pk_bf16_f32 v70, v16, v17
	v_cvt_pk_bf16_f32 v71, v18, v19
	global_store_dwordx2 v[68:69], v[70:71], off offset:128
	v_pk_mul_f32 v[20:21], v[20:21], v[64:65] op_sel_hi:[1,0]
	v_pk_mul_f32 v[22:23], v[22:23], v[64:65] op_sel_hi:[1,0]
	s_waitcnt vmcnt(15)
	v_lshlrev_b32_e32 v72, 16, v162
	v_and_b32_e32 v73, 0xffff0000, v162
	v_lshlrev_b32_e32 v74, 16, v163
	v_and_b32_e32 v75, 0xffff0000, v163
	v_pk_mul_f32 v[20:21], v[20:21], v[72:73]
	v_pk_mul_f32 v[22:23], v[22:23], v[74:75]
	v_cvt_pk_bf16_f32 v76, v20, v21
	v_cvt_pk_bf16_f32 v77, v22, v23
	global_store_dwordx2 v[68:69], v[76:77], off offset:144
	v_pk_mul_f32 v[24:25], v[24:25], v[64:65] op_sel_hi:[1,0]
	v_pk_mul_f32 v[26:27], v[26:27], v[64:65] op_sel_hi:[1,0]
	s_waitcnt vmcnt(15)
	v_lshlrev_b32_e32 v72, 16, v164
	v_and_b32_e32 v73, 0xffff0000, v164
	v_lshlrev_b32_e32 v74, 16, v165
	v_and_b32_e32 v75, 0xffff0000, v165
	v_pk_mul_f32 v[24:25], v[24:25], v[72:73]
	v_pk_mul_f32 v[26:27], v[26:27], v[74:75]
	v_cvt_pk_bf16_f32 v70, v24, v25
	v_cvt_pk_bf16_f32 v71, v26, v27
	global_store_dwordx2 v[68:69], v[70:71], off offset:160
	v_pk_mul_f32 v[28:29], v[28:29], v[64:65] op_sel_hi:[1,0]
	v_pk_mul_f32 v[30:31], v[30:31], v[64:65] op_sel_hi:[1,0]
	s_waitcnt vmcnt(15)
	v_lshlrev_b32_e32 v72, 16, v166
	v_and_b32_e32 v73, 0xffff0000, v166
	v_lshlrev_b32_e32 v74, 16, v167
	v_and_b32_e32 v75, 0xffff0000, v167
	v_pk_mul_f32 v[28:29], v[28:29], v[72:73]
	v_pk_mul_f32 v[30:31], v[30:31], v[74:75]
	v_cvt_pk_bf16_f32 v76, v28, v29
	v_cvt_pk_bf16_f32 v77, v30, v31
	global_store_dwordx2 v[68:69], v[76:77], off offset:176
	v_pk_mul_f32 v[0:1], v[0:1], v[64:65] op_sel_hi:[1,0]
	v_pk_mul_f32 v[2:3], v[2:3], v[64:65] op_sel_hi:[1,0]
	s_waitcnt vmcnt(15)
	v_lshlrev_b32_e32 v72, 16, v168
	v_and_b32_e32 v73, 0xffff0000, v168
	v_lshlrev_b32_e32 v74, 16, v169
	v_and_b32_e32 v75, 0xffff0000, v169
	v_pk_mul_f32 v[0:1], v[0:1], v[72:73]
	v_pk_mul_f32 v[2:3], v[2:3], v[74:75]
	v_cvt_pk_bf16_f32 v70, v0, v1
	v_cvt_pk_bf16_f32 v71, v2, v3
	global_store_dwordx2 v[68:69], v[70:71], off offset:192
	v_pk_mul_f32 v[4:5], v[4:5], v[64:65] op_sel_hi:[1,0]
	v_pk_mul_f32 v[6:7], v[6:7], v[64:65] op_sel_hi:[1,0]
	s_waitcnt vmcnt(15)
	v_lshlrev_b32_e32 v72, 16, v170
	v_and_b32_e32 v73, 0xffff0000, v170
	v_lshlrev_b32_e32 v74, 16, v171
	v_and_b32_e32 v75, 0xffff0000, v171
	v_pk_mul_f32 v[4:5], v[4:5], v[72:73]
	v_pk_mul_f32 v[6:7], v[6:7], v[74:75]
	v_cvt_pk_bf16_f32 v76, v4, v5
	v_cvt_pk_bf16_f32 v77, v6, v7
	global_store_dwordx2 v[68:69], v[76:77], off offset:208
	v_pk_mul_f32 v[8:9], v[8:9], v[64:65] op_sel_hi:[1,0]
	v_pk_mul_f32 v[10:11], v[10:11], v[64:65] op_sel_hi:[1,0]
	s_waitcnt vmcnt(15)
	v_lshlrev_b32_e32 v72, 16, v172
	v_and_b32_e32 v73, 0xffff0000, v172
	v_lshlrev_b32_e32 v74, 16, v173
	v_and_b32_e32 v75, 0xffff0000, v173
	v_pk_mul_f32 v[8:9], v[8:9], v[72:73]
	v_pk_mul_f32 v[10:11], v[10:11], v[74:75]
	v_cvt_pk_bf16_f32 v70, v8, v9
	v_cvt_pk_bf16_f32 v71, v10, v11
	global_store_dwordx2 v[68:69], v[70:71], off offset:224
	v_pk_mul_f32 v[12:13], v[12:13], v[64:65] op_sel_hi:[1,0]
	v_pk_mul_f32 v[14:15], v[14:15], v[64:65] op_sel_hi:[1,0]
	s_waitcnt vmcnt(15)
	v_lshlrev_b32_e32 v72, 16, v174
	v_and_b32_e32 v73, 0xffff0000, v174
	v_lshlrev_b32_e32 v74, 16, v175
	v_and_b32_e32 v75, 0xffff0000, v175
	v_pk_mul_f32 v[12:13], v[12:13], v[72:73]
	v_pk_mul_f32 v[14:15], v[14:15], v[74:75]
	v_cvt_pk_bf16_f32 v76, v12, v13
	v_cvt_pk_bf16_f32 v77, v14, v15
	global_store_dwordx2 v[68:69], v[76:77], off offset:240

.LBB0_49:
	s_or_b64 exec, exec, s[2:3]
	s_waitcnt lgkmcnt(0)
	s_barrier
	ds_read_b32 v0, v187 offset:44032
	s_mov_b64 s[2:3], -1
	s_waitcnt lgkmcnt(0)
	v_cmp_lt_i32_e32 vcc, s54, v0
	v_readfirstlane_b32 s4, v0
	s_cbranch_vccnz .LBB0_44
	s_ashr_i32 s5, s4, 4
	s_sub_i32 s2, 63, s5
	s_and_b32 s6, s4, 15
	v_lshl_add_u32 v212, s2, 7, v193
	s_lshl_b32 s66, s6, 13
	v_ashrrev_i32_e32 v213, 31, v212
	v_lshl_add_u64 v[0:1], s[66:67], 0, v[212:213]
	v_or_b32_e32 v0, v0, v192
	s_lshl_b32 s7, s2, 1
	v_mad_u64_u32 v[2:3], s[2:3], v0, s33, v[198:199]
	v_mad_i32_i24 v3, v1, s33, v3
	global_load_dwordx4 v[96:99], v[2:3], off
	global_load_dwordx4 v[100:103], v[2:3], off offset:32
	global_load_dwordx4 v[104:107], v[2:3], off offset:64
	global_load_dwordx4 v[108:111], v[2:3], off offset:96
	global_load_dwordx4 v[112:115], v[2:3], off offset:128
	global_load_dwordx4 v[116:119], v[2:3], off offset:160
	global_load_dwordx4 v[120:123], v[2:3], off offset:192
	global_load_dwordx4 v[124:127], v[2:3], off offset:224
	global_load_dwordx4 v[128:131], v[2:3], off offset:256
	global_load_dwordx4 v[132:135], v[2:3], off offset:288
	global_load_dwordx4 v[136:139], v[2:3], off offset:320
	global_load_dwordx4 v[140:143], v[2:3], off offset:352
	s_add_i32 s7, s7, 2
	s_lshl_b32 s66, s6, 21
	s_add_u32 s2, s8, s66
	s_addc_u32 s3, s9, 0
	v_lshl_add_u64 v[216:217], v[200:201], 0, s[66:67]
	v_lshl_add_u64 v[0:1], s[2:3], 0, v[202:203]
	v_lshl_add_u64 v[0:1], v[0:1], 0, v[186:187]
	v_add_co_u32_e32 v2, vcc, s79, v216
	global_load_dwordx4 v[148:151], v[0:1], off offset:64
	global_load_dwordx4 v[152:155], v[0:1], off offset:128
	global_load_dwordx4 v[156:159], v[204:205], off
	global_load_dwordx4 v[160:163], v[204:205], off offset:64
	global_load_dwordx4 v[164:167], v[0:1], off
	global_load_dwordx4 v[144:147], v[216:217], off
	v_addc_co_u32_e32 v3, vcc, 0, v217, vcc
	s_mov_b32 s4, 0x100000
	global_load_dwordx4 v[172:175], v[0:1], off offset:192
	global_load_dwordx4 v[168:171], v[2:3], off
	v_add_co_u32_e32 v0, vcc, s4, v216
	s_mov_b32 s4, 0x180000
	s_nop 0
	v_addc_co_u32_e32 v1, vcc, 0, v217, vcc
	v_add_co_u32_e32 v2, vcc, s4, v216
	v_mov_b32_e32 v14, v187
	s_nop 0
	v_addc_co_u32_e32 v3, vcc, 0, v217, vcc
	global_load_dwordx4 v[176:179], v[0:1], off
	global_load_dwordx4 v[180:183], v[2:3], off
	v_mov_b32_e32 v15, v187
	v_lshl_add_u64 v[218:219], s[2:3], 0, v[186:187]
	s_lshl_b32 s2, s5, 1
	v_mov_b32_e32 v0, v187
	v_mov_b32_e32 v1, v187
	v_mov_b32_e32 v2, v187
	v_mov_b32_e32 v3, v187
	v_mov_b32_e32 v4, v187
	v_mov_b32_e32 v5, v187
	v_mov_b32_e32 v6, v187
	v_mov_b32_e32 v7, v187
	v_mov_b32_e32 v8, v187
	v_mov_b32_e32 v9, v187
	v_mov_b32_e32 v10, v187
	v_mov_b32_e32 v11, v187
	v_mov_b32_e32 v12, v187
	v_mov_b32_e32 v13, v187
	v_mov_b64_e32 v[30:31], v[14:15]
	v_mov_b64_e32 v[46:47], v[14:15]
	v_mov_b64_e32 v[62:63], v[14:15]
	s_mov_b32 s15, 0
	v_or_b32_e32 v213, 31, v212
	v_or_b32_e32 v214, v212, v192
	v_readfirstlane_b32 s17, v213
	v_readfirstlane_b32 s18, v212
	s_sub_i32 s12, 0, s2
	v_mov_b32_e32 v240, 0xff800000
	v_mov_b32_e32 v215, 0
	s_movk_i32 s13, 0xff80
	v_mov_b64_e32 v[28:29], v[12:13]
	v_mov_b64_e32 v[26:27], v[10:11]
	v_mov_b64_e32 v[24:25], v[8:9]
	v_mov_b64_e32 v[22:23], v[6:7]
	v_mov_b64_e32 v[20:21], v[4:5]
	v_mov_b64_e32 v[18:19], v[2:3]
	v_mov_b64_e32 v[16:17], v[0:1]
	v_mov_b64_e32 v[44:45], v[12:13]
	v_mov_b64_e32 v[42:43], v[10:11]
	v_mov_b64_e32 v[40:41], v[8:9]
	v_mov_b64_e32 v[38:39], v[6:7]
	v_mov_b64_e32 v[36:37], v[4:5]
	v_mov_b64_e32 v[34:35], v[2:3]
	v_mov_b64_e32 v[32:33], v[0:1]
	v_mov_b64_e32 v[60:61], v[12:13]
	v_mov_b64_e32 v[58:59], v[10:11]
	v_mov_b64_e32 v[56:57], v[8:9]
	v_mov_b64_e32 v[54:55], v[6:7]
	v_mov_b64_e32 v[52:53], v[4:5]
	v_mov_b64_e32 v[50:51], v[2:3]
	v_mov_b64_e32 v[48:49], v[0:1]
.LBB0_51:
	s_add_i32 s2, s13, 0x81
	s_add_i32 s14, s15, 64
	s_cmp_lt_u32 s2, s7
	s_cselect_b32 s66, s14, s15
	v_add_u32_e32 v220, s66, v194
	v_add_u32_e32 v188, 0x6000, v238
	s_barrier
	s_waitcnt vmcnt(5)
	ds_write_b128 v237, v[164:167]
	ds_write_b128 v237, v[148:151] offset:64
	ds_write_b128 v237, v[152:155] offset:128
	s_waitcnt vmcnt(3)
	ds_write_b128 v237, v[172:175] offset:192
	ds_write_b128 v237, v[156:159] offset:256
	ds_write_b128 v237, v[160:163] offset:320
	v_ashrrev_i32_e32 v221, 31, v220
	ds_write2_b64 v188, v[144:145], v[146:147] offset0:128 offset1:130
	v_add_u32_e32 v188, 0x7000, v238
	v_lshlrev_b64 v[190:191], 8, v[220:221]
	v_lshlrev_b64 v[242:243], 7, v[220:221]
	s_waitcnt vmcnt(2)
	ds_write2_b64 v188, v[168:169], v[170:171] offset0:192 offset1:194
	v_add_u32_e32 v188, 0x8800, v238
	v_lshl_add_u64 v[190:191], v[218:219], 0, v[190:191]
	v_lshl_add_u64 v[242:243], v[206:207], 0, v[242:243]
	v_lshl_add_u64 v[252:253], s[66:67], 1, v[216:217]
	s_waitcnt vmcnt(1)
	ds_write2_b64 v188, v[176:177], v[178:179] offset1:2
	v_add_u32_e32 v188, 0x9800, v238
	v_add_u32_e32 v220, v195, v196
	s_waitcnt vmcnt(0)
	ds_write2_b64 v188, v[180:181], v[182:183] offset0:64 offset1:66
	s_waitcnt lgkmcnt(0)
	s_barrier
	s_cmp_le_i32 s15, s17
	s_cbranch_scc0 .Lattn_ld
	ds_read_b128 v[244:247], v220
	ds_read_b128 v[248:251], v220 offset:32
	ds_read_b128 v[222:225], v220 offset:64
	ds_read_b128 v[230:233], v220 offset:96
	ds_read_b128 v[64:67], v220 offset:128
	ds_read_b128 v[68:71], v220 offset:160
	ds_read_b128 v[72:75], v220 offset:192
	ds_read_b128 v[76:79], v220 offset:224
.Lattn_ld:
	global_load_dwordx4 v[164:167], v[190:191], off
	global_load_dwordx4 v[148:151], v[190:191], off offset:64
	global_load_dwordx4 v[152:155], v[190:191], off offset:128
	global_load_dwordx4 v[172:175], v[190:191], off offset:192
	global_load_dwordx4 v[156:159], v[242:243], off
	global_load_dwordx4 v[160:163], v[242:243], off offset:64
	v_add_co_u32_e32 v190, vcc, s79, v252
	s_nop 1
	v_addc_co_u32_e32 v191, vcc, 0, v253, vcc
	global_load_dwordx4 v[144:147], v[252:253], off
	global_load_dwordx4 v[168:171], v[190:191], off
	v_add_co_u32_e32 v190, vcc, 0x100000, v252
	s_nop 1
	v_addc_co_u32_e32 v191, vcc, 0, v253, vcc
	v_add_co_u32_e32 v242, vcc, 0x180000, v252
	s_nop 1
	v_addc_co_u32_e32 v243, vcc, 0, v253, vcc
	global_load_dwordx4 v[176:179], v[190:191], off
	global_load_dwordx4 v[180:183], v[242:243], off
	s_cmp_le_i32 s15, s17
	s_cbranch_scc0 .LBB0_57
	s_setprio 1
	s_waitcnt lgkmcnt(7)
	v_mfma_f32_32x32x16_bf16 v[80:95], v[244:247], v[96:99], 0
	ds_read_b128 v[244:247], v220 offset:256
	s_waitcnt lgkmcnt(7)
	v_mfma_f32_32x32x16_bf16 v[80:95], v[248:251], v[100:103], v[80:95]
	ds_read_b128 v[248:251], v220 offset:288
	s_waitcnt lgkmcnt(7)
	v_mfma_f32_32x32x16_bf16 v[80:95], v[222:225], v[104:107], v[80:95]
	ds_read_b128 v[222:225], v220 offset:320
	s_waitcnt lgkmcnt(7)
	v_mfma_f32_32x32x16_bf16 v[80:95], v[230:233], v[108:111], v[80:95]
	ds_read_b128 v[230:233], v220 offset:352
	s_waitcnt lgkmcnt(7)
	v_mfma_f32_32x32x16_bf16 v[80:95], v[64:67], v[112:115], v[80:95]
	s_waitcnt lgkmcnt(6)
	v_mfma_f32_32x32x16_bf16 v[80:95], v[68:71], v[116:119], v[80:95]
	s_waitcnt lgkmcnt(5)
	v_mfma_f32_32x32x16_bf16 v[80:95], v[72:75], v[120:123], v[80:95]
	s_waitcnt lgkmcnt(4)
	v_mfma_f32_32x32x16_bf16 v[80:95], v[76:79], v[124:127], v[80:95]
	s_waitcnt lgkmcnt(3)
	v_mfma_f32_32x32x16_bf16 v[80:95], v[244:247], v[128:131], v[80:95]
	ds_read_b128 v[244:247], v220 offset:12800
	s_waitcnt lgkmcnt(3)
	v_mfma_f32_32x32x16_bf16 v[80:95], v[248:251], v[132:135], v[80:95]
	ds_read_b128 v[248:251], v220 offset:12832
	s_waitcnt lgkmcnt(3)
	v_mfma_f32_32x32x16_bf16 v[80:95], v[222:225], v[136:139], v[80:95]
	ds_read_b128 v[222:225], v220 offset:12864
	s_waitcnt lgkmcnt(3)
	v_mfma_f32_32x32x16_bf16 v[80:95], v[230:233], v[140:143], v[80:95]
	ds_read_b128 v[230:233], v220 offset:12896
	s_waitcnt lgkmcnt(3)
	v_mfma_f32_32x32x16_bf16 v[64:79], v[244:247], v[96:99], 0
	ds_read_b128 v[244:247], v220 offset:12928
	s_waitcnt lgkmcnt(3)
	v_mfma_f32_32x32x16_bf16 v[64:79], v[248:251], v[100:103], v[64:79]
	ds_read_b128 v[248:251], v220 offset:12960
	s_waitcnt lgkmcnt(3)
	v_mfma_f32_32x32x16_bf16 v[64:79], v[222:225], v[104:107], v[64:79]
	ds_read_b128 v[222:225], v220 offset:12992
	s_waitcnt lgkmcnt(3)
	v_mfma_f32_32x32x16_bf16 v[64:79], v[230:233], v[108:111], v[64:79]
	ds_read_b128 v[230:233], v220 offset:13024
	s_waitcnt lgkmcnt(3)
	v_mfma_f32_32x32x16_bf16 v[64:79], v[244:247], v[112:115], v[64:79]
	ds_read_b128 v[244:247], v220 offset:13056
	s_waitcnt lgkmcnt(3)
	v_mfma_f32_32x32x16_bf16 v[64:79], v[248:251], v[116:119], v[64:79]
	ds_read_b128 v[248:251], v220 offset:13088
	s_waitcnt lgkmcnt(3)
	v_mfma_f32_32x32x16_bf16 v[64:79], v[222:225], v[120:123], v[64:79]
	ds_read_b128 v[222:225], v220 offset:13120
	s_waitcnt lgkmcnt(3)
	v_mfma_f32_32x32x16_bf16 v[64:79], v[230:233], v[124:127], v[64:79]
	ds_read_b128 v[230:233], v220 offset:13152
	s_waitcnt lgkmcnt(3)
	v_mfma_f32_32x32x16_bf16 v[64:79], v[244:247], v[128:131], v[64:79]
	s_waitcnt lgkmcnt(2)
	v_mfma_f32_32x32x16_bf16 v[64:79], v[248:251], v[132:135], v[64:79]
	s_waitcnt lgkmcnt(1)
	v_mfma_f32_32x32x16_bf16 v[64:79], v[222:225], v[136:139], v[64:79]
	s_waitcnt lgkmcnt(0)
	v_mfma_f32_32x32x16_bf16 v[64:79], v[230:233], v[140:143], v[64:79]
	s_setprio 0
	ds_read_b128 v[244:247], v239 offset:25600
	ds_read_b128 v[248:251], v239 offset:30208
	ds_read_b128 v[222:225], v239 offset:34816
	ds_read_b128 v[230:233], v239 offset:39424
	s_add_i32 s4, s15, 63
	s_cmp_gt_i32 s4, s18
	s_cbranch_scc0 .Lattn_nomask
	v_add_u32_e32 v220, s15, v197
	v_cmp_gt_i32_e32 vcc, v220, v214
	s_nop 1
	v_cndmask_b32_e32 v221, v80, v234, vcc
	v_cmp_lt_i32_e32 vcc, v220, v214
	s_nop 1
	v_cndmask_b32_e32 v80, v221, v80, vcc
	v_add_u32_e32 v221, 2, v220
	v_cndmask_b32_e32 v81, v234, v81, vcc
	v_cmp_le_i32_e32 vcc, v221, v214
	v_add_u32_e32 v221, 3, v220
	s_nop 0
	v_cndmask_b32_e32 v82, v234, v82, vcc
	v_cmp_le_i32_e32 vcc, v221, v214
	v_add_u32_e32 v221, 8, v220
	s_nop 0
	v_cndmask_b32_e32 v83, v234, v83, vcc
	v_cmp_le_i32_e32 vcc, v221, v214
	v_add_u32_e32 v221, 9, v220
	s_nop 0
	v_cndmask_b32_e32 v84, v234, v84, vcc
	v_cmp_le_i32_e32 vcc, v221, v214
	v_add_u32_e32 v221, 10, v220
	s_nop 0
	v_cndmask_b32_e32 v85, v234, v85, vcc
	v_cmp_le_i32_e32 vcc, v221, v214
	v_add_u32_e32 v221, 11, v220
	s_nop 0
	v_cndmask_b32_e32 v86, v234, v86, vcc
	v_cmp_le_i32_e32 vcc, v221, v214
	v_add_u32_e32 v221, 16, v220
	s_nop 0
	v_cndmask_b32_e32 v87, v234, v87, vcc
	v_cmp_le_i32_e32 vcc, v221, v214
	v_add_u32_e32 v221, 17, v220
	s_nop 0
	v_cndmask_b32_e32 v88, v234, v88, vcc
	v_cmp_le_i32_e32 vcc, v221, v214
	v_add_u32_e32 v221, 18, v220
	s_nop 0
	v_cndmask_b32_e32 v89, v234, v89, vcc
	v_cmp_le_i32_e32 vcc, v221, v214
	v_add_u32_e32 v221, 19, v220
	s_nop 0
	v_cndmask_b32_e32 v90, v234, v90, vcc
	v_cmp_le_i32_e32 vcc, v221, v214
	v_add_u32_e32 v221, 24, v220
	s_nop 0
	v_cndmask_b32_e32 v91, v234, v91, vcc
	v_cmp_le_i32_e32 vcc, v221, v214
	v_add_u32_e32 v221, 25, v220
	s_nop 0
	v_cndmask_b32_e32 v92, v234, v92, vcc
	v_cmp_le_i32_e32 vcc, v221, v214
	v_add_u32_e32 v221, 26, v220
	s_nop 0
	v_cndmask_b32_e32 v93, v234, v93, vcc
	v_cmp_le_i32_e32 vcc, v221, v214
	v_add_u32_e32 v221, 27, v220
	s_nop 0
	v_cndmask_b32_e32 v94, v234, v94, vcc
	v_cmp_le_i32_e32 vcc, v221, v214
	v_add_u32_e32 v221, 32, v220
	s_nop 0
	v_cndmask_b32_e32 v95, v234, v95, vcc
	v_cmp_le_i32_e32 vcc, v221, v214
	v_add_u32_e32 v221, 33, v220
	s_nop 0
	v_cndmask_b32_e32 v64, v234, v64, vcc
	v_cmp_le_i32_e32 vcc, v221, v214
	v_add_u32_e32 v221, 34, v220
	s_nop 0
	v_cndmask_b32_e32 v65, v234, v65, vcc
	v_cmp_le_i32_e32 vcc, v221, v214
	v_add_u32_e32 v221, 35, v220
	s_nop 0
	v_cndmask_b32_e32 v66, v234, v66, vcc
	v_cmp_le_i32_e32 vcc, v221, v214
	v_add_u32_e32 v221, 40, v220
	s_nop 0
	v_cndmask_b32_e32 v67, v234, v67, vcc
	v_cmp_le_i32_e32 vcc, v221, v214
	v_add_u32_e32 v221, 41, v220
	s_nop 0
	v_cndmask_b32_e32 v68, v234, v68, vcc
	v_cmp_le_i32_e32 vcc, v221, v214
	v_add_u32_e32 v221, 42, v220
	s_nop 0
	v_cndmask_b32_e32 v69, v234, v69, vcc
	v_cmp_le_i32_e32 vcc, v221, v214
	v_add_u32_e32 v221, 43, v220
	s_nop 0
	v_cndmask_b32_e32 v70, v234, v70, vcc
	v_cmp_le_i32_e32 vcc, v221, v214
	v_add_u32_e32 v221, 48, v220
	s_nop 0
	v_cndmask_b32_e32 v71, v234, v71, vcc
	v_cmp_le_i32_e32 vcc, v221, v214
	v_add_u32_e32 v221, 49, v220
	s_nop 0
	v_cndmask_b32_e32 v72, v234, v72, vcc
	v_cmp_le_i32_e32 vcc, v221, v214
	v_add_u32_e32 v221, 50, v220
	s_nop 0
	v_cndmask_b32_e32 v73, v234, v73, vcc
	v_cmp_le_i32_e32 vcc, v221, v214
	v_add_u32_e32 v221, 51, v220
	s_nop 0
	v_cndmask_b32_e32 v74, v234, v74, vcc
	v_cmp_le_i32_e32 vcc, v221, v214
	v_add_u32_e32 v221, 56, v220
	s_nop 0
	v_cndmask_b32_e32 v75, v234, v75, vcc
	v_cmp_le_i32_e32 vcc, v221, v214
	v_add_u32_e32 v221, 57, v220
	s_nop 0
	v_cndmask_b32_e32 v76, v234, v76, vcc
	v_cmp_le_i32_e32 vcc, v221, v214
	v_add_u32_e32 v221, 58, v220
	v_add_u32_e32 v220, 59, v220
	v_cndmask_b32_e32 v77, v234, v77, vcc
	v_cmp_le_i32_e32 vcc, v221, v214
	s_nop 1
	v_cndmask_b32_e32 v78, v234, v78, vcc
	v_cmp_le_i32_e32 vcc, v220, v214
	s_nop 1
	v_cndmask_b32_e32 v79, v234, v79, vcc
.Lattn_nomask:
	v_max3_f32 v220, v80, v81, v82
	v_max3_f32 v220, v220, v83, v84
	v_max3_f32 v220, v220, v85, v86
	v_max3_f32 v220, v220, v87, v88
	v_max3_f32 v220, v220, v89, v90
	v_max3_f32 v220, v220, v91, v92
	v_max3_f32 v220, v220, v93, v94
	v_max3_f32 v220, v220, v95, v64
	v_max3_f32 v220, v220, v65, v66
	v_max3_f32 v220, v220, v67, v68
	v_max3_f32 v220, v220, v69, v70
	v_max3_f32 v220, v220, v71, v72
	v_max3_f32 v220, v220, v73, v74
	v_max3_f32 v220, v220, v75, v76
	v_max3_f32 v220, v220, v77, v78
	v_max_f32_e32 v220, v220, v79
	v_mov_b32_e32 v221, v220
	s_nop 1
	v_permlane32_swap_b32_e32 v220, v221
	v_max_f32_e32 v220, v220, v221
	v_add_f32_e32 v221, 0x41000000, v240
	v_cmp_gt_f32_e32 vcc, v220, v221
	s_nop 1
	v_cndmask_b32_e32 v241, v240, v220, vcc
	v_sub_f32_e32 v220, v240, v241
	v_exp_f32_e32 v220, v220
	v_cmp_neq_f32_e32 vcc, v241, v240
	s_cbranch_vccz .Lattn_noresc
	v_pk_mul_f32 v[62:63], v[62:63], v[220:221] op_sel_hi:[1,0]
	v_pk_mul_f32 v[60:61], v[60:61], v[220:221] op_sel_hi:[1,0]
	v_pk_mul_f32 v[58:59], v[58:59], v[220:221] op_sel_hi:[1,0]
	v_pk_mul_f32 v[56:57], v[56:57], v[220:221] op_sel_hi:[1,0]
	v_pk_mul_f32 v[54:55], v[54:55], v[220:221] op_sel_hi:[1,0]
	v_pk_mul_f32 v[52:53], v[52:53], v[220:221] op_sel_hi:[1,0]
	v_pk_mul_f32 v[50:51], v[50:51], v[220:221] op_sel_hi:[1,0]
	v_pk_mul_f32 v[48:49], v[48:49], v[220:221] op_sel_hi:[1,0]
	v_pk_mul_f32 v[46:47], v[46:47], v[220:221] op_sel_hi:[1,0]
	v_pk_mul_f32 v[44:45], v[44:45], v[220:221] op_sel_hi:[1,0]
	v_pk_mul_f32 v[42:43], v[42:43], v[220:221] op_sel_hi:[1,0]
	v_pk_mul_f32 v[40:41], v[40:41], v[220:221] op_sel_hi:[1,0]
	v_pk_mul_f32 v[38:39], v[38:39], v[220:221] op_sel_hi:[1,0]
	v_pk_mul_f32 v[36:37], v[36:37], v[220:221] op_sel_hi:[1,0]
	v_pk_mul_f32 v[34:35], v[34:35], v[220:221] op_sel_hi:[1,0]
	v_pk_mul_f32 v[32:33], v[32:33], v[220:221] op_sel_hi:[1,0]
	v_pk_mul_f32 v[30:31], v[30:31], v[220:221] op_sel_hi:[1,0]
	v_pk_mul_f32 v[28:29], v[28:29], v[220:221] op_sel_hi:[1,0]
	v_pk_mul_f32 v[26:27], v[26:27], v[220:221] op_sel_hi:[1,0]
	v_pk_mul_f32 v[24:25], v[24:25], v[220:221] op_sel_hi:[1,0]
	v_pk_mul_f32 v[22:23], v[22:23], v[220:221] op_sel_hi:[1,0]
	v_pk_mul_f32 v[20:21], v[20:21], v[220:221] op_sel_hi:[1,0]
	v_pk_mul_f32 v[18:19], v[18:19], v[220:221] op_sel_hi:[1,0]
	v_pk_mul_f32 v[16:17], v[16:17], v[220:221] op_sel_hi:[1,0]
	v_pk_mul_f32 v[14:15], v[14:15], v[220:221] op_sel_hi:[1,0]
	v_pk_mul_f32 v[12:13], v[12:13], v[220:221] op_sel_hi:[1,0]
	v_pk_mul_f32 v[10:11], v[10:11], v[220:221] op_sel_hi:[1,0]
	v_pk_mul_f32 v[8:9], v[8:9], v[220:221] op_sel_hi:[1,0]
	v_pk_mul_f32 v[6:7], v[6:7], v[220:221] op_sel_hi:[1,0]
	v_pk_mul_f32 v[4:5], v[4:5], v[220:221] op_sel_hi:[1,0]
	v_pk_mul_f32 v[2:3], v[2:3], v[220:221] op_sel_hi:[1,0]
	v_pk_mul_f32 v[0:1], v[0:1], v[220:221] op_sel_hi:[1,0]
.Lattn_noresc:
	v_sub_f32_e32 v80, v80, v241
	v_sub_f32_e32 v81, v81, v241
	v_sub_f32_e32 v82, v82, v241
	v_sub_f32_e32 v83, v83, v241
	v_sub_f32_e32 v84, v84, v241
	v_sub_f32_e32 v85, v85, v241
	v_sub_f32_e32 v86, v86, v241
	v_sub_f32_e32 v87, v87, v241
	v_sub_f32_e32 v88, v88, v241
	v_sub_f32_e32 v89, v89, v241
	v_sub_f32_e32 v90, v90, v241
	v_sub_f32_e32 v91, v91, v241
	v_sub_f32_e32 v92, v92, v241
	v_sub_f32_e32 v93, v93, v241
	v_sub_f32_e32 v94, v94, v241
	v_sub_f32_e32 v95, v95, v241
	v_sub_f32_e32 v64, v64, v241
	v_sub_f32_e32 v65, v65, v241
	v_sub_f32_e32 v66, v66, v241
	v_sub_f32_e32 v67, v67, v241
	v_sub_f32_e32 v68, v68, v241
	v_sub_f32_e32 v69, v69, v241
	v_sub_f32_e32 v70, v70, v241
	v_sub_f32_e32 v71, v71, v241
	v_sub_f32_e32 v72, v72, v241
	v_sub_f32_e32 v73, v73, v241
	v_sub_f32_e32 v74, v74, v241
	v_sub_f32_e32 v75, v75, v241
	v_sub_f32_e32 v76, v76, v241
	v_sub_f32_e32 v77, v77, v241
	v_sub_f32_e32 v78, v78, v241
	v_sub_f32_e32 v79, v79, v241
	v_exp_f32_e32 v80, v80
	v_exp_f32_e32 v81, v81
	v_exp_f32_e32 v82, v82
	v_add_f32_e32 v221, v80, v81
	v_exp_f32_e32 v83, v83
	v_add_f32_e32 v221, v221, v82
	v_exp_f32_e32 v84, v84
	v_add_f32_e32 v221, v221, v83
	v_exp_f32_e32 v85, v85
	v_add_f32_e32 v221, v221, v84
	v_exp_f32_e32 v86, v86
	v_add_f32_e32 v221, v221, v85
	v_exp_f32_e32 v87, v87
	v_add_f32_e32 v221, v221, v86
	v_exp_f32_e32 v88, v88
	v_add_f32_e32 v221, v221, v87
	v_exp_f32_e32 v89, v89
	v_add_f32_e32 v221, v221, v88
	v_exp_f32_e32 v90, v90
	v_add_f32_e32 v221, v221, v89
	v_exp_f32_e32 v91, v91
	v_add_f32_e32 v221, v221, v90
	v_exp_f32_e32 v92, v92
	v_add_f32_e32 v221, v221, v91
	v_exp_f32_e32 v93, v93
	v_add_f32_e32 v221, v221, v92
	v_exp_f32_e32 v94, v94
	v_add_f32_e32 v221, v221, v93
	v_exp_f32_e32 v95, v95
	v_add_f32_e32 v221, v221, v94
	v_exp_f32_e32 v64, v64
	v_add_f32_e32 v221, v221, v95
	v_exp_f32_e32 v65, v65
	v_add_f32_e32 v221, v221, v64
	v_exp_f32_e32 v66, v66
	v_add_f32_e32 v221, v221, v65
	v_exp_f32_e32 v67, v67
	v_add_f32_e32 v221, v221, v66
	v_exp_f32_e32 v68, v68
	v_add_f32_e32 v221, v221, v67
	v_exp_f32_e32 v69, v69
	v_add_f32_e32 v221, v221, v68
	v_exp_f32_e32 v70, v70
	v_add_f32_e32 v221, v221, v69
	v_exp_f32_e32 v71, v71
	v_add_f32_e32 v221, v221, v70
	v_exp_f32_e32 v72, v72
	v_add_f32_e32 v221, v221, v71
	v_exp_f32_e32 v73, v73
	v_add_f32_e32 v221, v221, v72
	v_exp_f32_e32 v74, v74
	v_add_f32_e32 v221, v221, v73
	v_exp_f32_e32 v75, v75
	v_add_f32_e32 v221, v221, v74
	v_exp_f32_e32 v76, v76
	v_add_f32_e32 v221, v221, v75
	v_exp_f32_e32 v77, v77
	v_add_f32_e32 v221, v221, v76
	v_exp_f32_e32 v78, v78
	v_add_f32_e32 v221, v221, v77
	v_exp_f32_e32 v79, v79
	v_add_f32_e32 v221, v221, v78
	s_nop 0
	v_add_f32_e32 v221, v221, v79
	v_fmac_f32_e32 v221, v215, v220
	v_cvt_pk_bf16_f32 v80, v80, v81
	v_cvt_pk_bf16_f32 v81, v82, v83
	v_cvt_pk_bf16_f32 v82, v84, v85
	v_cvt_pk_bf16_f32 v83, v86, v87
	v_cvt_pk_bf16_f32 v88, v88, v89
	v_cvt_pk_bf16_f32 v89, v90, v91
	v_cvt_pk_bf16_f32 v90, v92, v93
	v_cvt_pk_bf16_f32 v91, v94, v95
	v_cvt_pk_bf16_f32 v64, v64, v65
	v_cvt_pk_bf16_f32 v65, v66, v67
	v_cvt_pk_bf16_f32 v66, v68, v69
	v_cvt_pk_bf16_f32 v67, v70, v71
	v_cvt_pk_bf16_f32 v72, v72, v73
	v_cvt_pk_bf16_f32 v73, v74, v75
	v_cvt_pk_bf16_f32 v74, v76, v77
	v_cvt_pk_bf16_f32 v75, v78, v79
	v_mov_b32_e32 v215, v221
	v_mov_b32_e32 v240, v241
	ds_read_b128 v[84:87], v239 offset:25632
	ds_read_b128 v[92:95], v239 offset:30240
	ds_read_b128 v[68:71], v239 offset:34848
	ds_read_b128 v[76:79], v239 offset:39456
	s_setprio 1
	s_waitcnt lgkmcnt(7)
	v_mfma_f32_32x32x16_bf16 v[48:63], v[244:247], v[80:83], v[48:63]
	ds_read_b128 v[244:247], v239 offset:25664
	s_waitcnt lgkmcnt(7)
	v_mfma_f32_32x32x16_bf16 v[32:47], v[248:251], v[80:83], v[32:47]
	ds_read_b128 v[248:251], v239 offset:30272
	s_waitcnt lgkmcnt(7)
	v_mfma_f32_32x32x16_bf16 v[16:31], v[222:225], v[80:83], v[16:31]
	ds_read_b128 v[222:225], v239 offset:34880
	s_waitcnt lgkmcnt(7)
	v_mfma_f32_32x32x16_bf16 v[0:15], v[230:233], v[80:83], v[0:15]
	ds_read_b128 v[230:233], v239 offset:39488
	s_waitcnt lgkmcnt(7)
	v_mfma_f32_32x32x16_bf16 v[48:63], v[84:87], v[88:91], v[48:63]
	ds_read_b128 v[84:87], v239 offset:25696
	s_waitcnt lgkmcnt(7)
	v_mfma_f32_32x32x16_bf16 v[32:47], v[92:95], v[88:91], v[32:47]
	ds_read_b128 v[92:95], v239 offset:30304
	s_waitcnt lgkmcnt(7)
	v_mfma_f32_32x32x16_bf16 v[16:31], v[68:71], v[88:91], v[16:31]
	ds_read_b128 v[68:71], v239 offset:34912
	s_waitcnt lgkmcnt(7)
	v_mfma_f32_32x32x16_bf16 v[0:15], v[76:79], v[88:91], v[0:15]
	ds_read_b128 v[76:79], v239 offset:39520
	s_waitcnt lgkmcnt(7)
	v_mfma_f32_32x32x16_bf16 v[48:63], v[244:247], v[64:67], v[48:63]
	s_waitcnt lgkmcnt(6)
	v_mfma_f32_32x32x16_bf16 v[32:47], v[248:251], v[64:67], v[32:47]
	s_waitcnt lgkmcnt(5)
	v_mfma_f32_32x32x16_bf16 v[16:31], v[222:225], v[64:67], v[16:31]
	s_waitcnt lgkmcnt(4)
	v_mfma_f32_32x32x16_bf16 v[0:15], v[230:233], v[64:67], v[0:15]
	s_waitcnt lgkmcnt(3)
	v_mfma_f32_32x32x16_bf16 v[48:63], v[84:87], v[72:75], v[48:63]
	s_waitcnt lgkmcnt(2)
	v_mfma_f32_32x32x16_bf16 v[32:47], v[92:95], v[72:75], v[32:47]
	s_waitcnt lgkmcnt(1)
	v_mfma_f32_32x32x16_bf16 v[16:31], v[68:71], v[72:75], v[16:31]
	s_waitcnt lgkmcnt(0)
	v_mfma_f32_32x32x16_bf16 v[0:15], v[76:79], v[72:75], v[0:15]
	s_setprio 0
.LBB0_57:
	s_add_i32 s13, s13, 1
	s_cmp_eq_u32 s12, s13
	s_cbranch_scc1 .LBB0_43
	s_mov_b32 s15, s14
	s_branch .LBB0_51
.LBB0_59:
	v_mov_b32_e32 v188, 0x358637bd
	v_mov_b64_e32 v[190:191], 0x3d81000
	v_mov_b32_e32 v222, 0x1000
	v_mov_b32_e32 v223, 0x2000
	v_mov_b32_e32 v224, 0xff03000
	v_mov_b32_e32 v225, 1
	v_xor_b32_e32 v230, 8, v226
	v_xor_b32_e32 v231, 4, v226
	v_xor_b32_e32 v232, 2, v226
	v_xor_b32_e32 v233, 1, v226
	v_mov_b32_e32 v242, v187
	v_mov_b32_e32 v243, v187
	s_mov_b64 s[0:1], 0
